# sliding-window deferred-max loop QK: three kc=1 K fragment reads issued with the first batch (7 in flight) and counted lgkmcnt instead of a full drain before the second MFMA group
# baseline (speedup 1.0000x reference)
; #define LAS __attribute__((address_space(3)))
; #pragma unroll
;     for (int sub = 0; sub < 4; ++sub) { s[0][sub] = (f32x4){init0, init0, init0, init0}; s[1][sub] = (f32x4){init1, init1, init1, init1}; }
; #pragma unroll
;     for (int kc = 0; kc < 4; ++kc) {
;         bf16x8 kf[4];
; #pragma unroll
;         for (int sub = 0; sub < 4; ++sub) kf[sub] = *(const LAS bf16x8*)(buf + (16 * sub + ql) * KT_PITCH + kc * 64 + g * 16);
; #pragma unroll
;         for (int sub = 0; sub < 4; ++sub) {
;             s[0][sub] = __builtin_amdgcn_mfma_f32_16x16x32_bf16(kf[sub], qf[0][kc], s[0][sub], 0, 0, 0);
;             s[1][sub] = __builtin_amdgcn_mfma_f32_16x16x32_bf16(kf[sub], qf[1][kc], s[1][sub], 0, 0, 0);
;         }
;         if (kc & 1) asm volatile("" ::: "memory");
;     }
; }
; template <int MODE, bool DEFER> ...
;     ...
;     if (DEFER) qk_tile2(s, qf, buf, ql, g, take[0] ? -mrun[0] : -__builtin_inff(), take[1] ? -mrun[1] : -__builtin_inff());
;     else qk_tile2(s, qf, buf, ql, g);
;     if (tile < tile_hi) stage_load<true, true>(R, Kg, VTg, vpitch, (tile + 1) * 64, tid);
;     u32x4 pk[2][2];
;     if (DEFER) {
;         float m0 = local_max16(s[0]), m1 = local_max16(s[1]);
;         if (__any(m0 > DEFER_THRESH || m1 > DEFER_THRESH)) {
.LBB0_1032:
	s_bitcmp1_b32 s1, 0
	s_cselect_b32 s7, 0x8c00, 0
	s_add_i32 s8, s7, 0
	v_add3_u32 v0, s8, v149, v201
	s_waitcnt vmcnt(1)
	ds_read_b128 v[108:111], v0
	s_waitcnt vmcnt(0)
	ds_read_b128 v[112:115], v0 offset:4352
	ds_read_b128 v[116:119], v0 offset:8704
	ds_read_b128 v[120:123], v0 offset:13056
	ds_read_b128 v[144:147], v0 offset:64
	ds_read_b128 v[140:143], v0 offset:4416
	ds_read_b128 v[136:139], v0 offset:8768
	v_xor_b32_e32 v100, 0x80000000, v175
	v_xor_b32_e32 v104, 0x80000000, v174
	v_mov_b32_e32 v105, v104
	v_mov_b32_e32 v106, v104
	v_mov_b32_e32 v107, v104
	v_mov_b32_e32 v101, v100
	v_mov_b32_e32 v102, v100
	v_mov_b32_e32 v103, v100
	s_waitcnt lgkmcnt(6)
	v_mfma_f32_16x16x32_bf16 v[124:127], v[108:111], v[4:7], v[104:107]
	s_ashr_i32 s7, s6, 31
	v_lshl_add_u64 v[2:3], s[6:7], 1, v[172:173]
	v_mfma_f32_16x16x32_bf16 v[108:111], v[108:111], v[20:23], v[100:103]
	s_waitcnt lgkmcnt(5)
	v_mfma_f32_16x16x32_bf16 v[128:131], v[112:115], v[4:7], v[104:107]
	v_mfma_f32_16x16x32_bf16 v[112:115], v[112:115], v[20:23], v[100:103]
	s_waitcnt lgkmcnt(4)
	v_mfma_f32_16x16x32_bf16 v[132:135], v[116:119], v[4:7], v[104:107]
	v_mfma_f32_16x16x32_bf16 v[116:119], v[116:119], v[20:23], v[100:103]
	s_waitcnt lgkmcnt(3)
	v_mfma_f32_16x16x32_bf16 v[104:107], v[120:123], v[4:7], v[104:107]
	v_mfma_f32_16x16x32_bf16 v[100:103], v[120:123], v[20:23], v[100:103]
	ds_read_b128 v[120:123], v0 offset:13120
	s_waitcnt lgkmcnt(3)
	v_mfma_f32_16x16x32_bf16 v[124:127], v[144:147], v[8:11], v[124:127]
	v_mfma_f32_16x16x32_bf16 v[108:111], v[144:147], v[24:27], v[108:111]
	s_waitcnt lgkmcnt(2)
	v_mfma_f32_16x16x32_bf16 v[128:131], v[140:143], v[8:11], v[128:131]
	v_mfma_f32_16x16x32_bf16 v[112:115], v[140:143], v[24:27], v[112:115]
	s_waitcnt lgkmcnt(1)
	v_mfma_f32_16x16x32_bf16 v[132:135], v[136:139], v[8:11], v[132:135]
	v_mfma_f32_16x16x32_bf16 v[116:119], v[136:139], v[24:27], v[116:119]
	s_waitcnt lgkmcnt(0)
	v_mfma_f32_16x16x32_bf16 v[104:107], v[120:123], v[8:11], v[104:107]
	v_mfma_f32_16x16x32_bf16 v[100:103], v[120:123], v[24:27], v[100:103]
	ds_read_b128 v[120:123], v0 offset:128
	ds_read_b128 v[136:139], v0 offset:4480
	ds_read_b128 v[140:143], v0 offset:8832
	ds_read_b128 v[144:147], v0 offset:13184
	s_waitcnt lgkmcnt(3)
	v_mfma_f32_16x16x32_bf16 v[124:127], v[120:123], v[12:15], v[124:127]
	v_mfma_f32_16x16x32_bf16 v[108:111], v[120:123], v[28:31], v[108:111]
	s_waitcnt lgkmcnt(2)
	v_mfma_f32_16x16x32_bf16 v[120:123], v[136:139], v[12:15], v[128:131]
	v_mfma_f32_16x16x32_bf16 v[112:115], v[136:139], v[28:31], v[112:115]
	ds_read_b128 v[176:179], v0 offset:13248
	ds_read_b128 v[180:183], v0 offset:8896
	ds_read_b128 v[136:139], v0 offset:4544
	ds_read_b128 v[128:131], v0 offset:192
	s_waitcnt lgkmcnt(5)
	v_mfma_f32_16x16x32_bf16 v[116:119], v[140:143], v[28:31], v[116:119]
	s_waitcnt lgkmcnt(4)
	v_mfma_f32_16x16x32_bf16 v[100:103], v[144:147], v[28:31], v[100:103]
	v_mfma_f32_16x16x32_bf16 v[132:135], v[140:143], v[12:15], v[132:135]
	v_mfma_f32_16x16x32_bf16 v[104:107], v[144:147], v[12:15], v[104:107]
	s_waitcnt lgkmcnt(0)
	v_mfma_f32_16x16x32_bf16 v[144:147], v[128:131], v[16:19], v[124:127]
	v_max3_f32 v0, v144, v144, v145
	s_nop 0
	v_max3_f32 v0, v0, v146, v147
	v_mfma_f32_16x16x32_bf16 v[128:131], v[128:131], v[32:35], v[108:111]
	v_mfma_f32_16x16x32_bf16 v[140:143], v[136:139], v[16:19], v[120:123]
	s_nop 1
	v_add_u32_e32 v108, s6, v152
	v_ashrrev_i32_e32 v109, 31, v108
	v_lshlrev_b64 v[108:109], 8, v[108:109]
	v_mfma_f32_16x16x32_bf16 v[120:123], v[180:183], v[32:35], v[116:119]
	v_lshl_add_u64 v[108:109], v[168:169], 0, v[108:109]
	global_load_dwordx4 v[108:111], v[108:109], off
	v_max3_f32 v0, v0, v140, v141
	v_mfma_f32_16x16x32_bf16 v[116:119], v[176:179], v[32:35], v[100:103]
	v_max3_f32 v0, v0, v142, v143
	v_mfma_f32_16x16x32_bf16 v[124:127], v[136:139], v[32:35], v[112:115]
	s_nop 1
	v_add_u32_e32 v100, s6, v150
	v_ashrrev_i32_e32 v101, 31, v100
	v_lshlrev_b64 v[100:101], 8, v[100:101]
	v_mfma_f32_16x16x32_bf16 v[136:139], v[180:183], v[16:19], v[132:135]
	v_lshl_add_u64 v[100:101], v[168:169], 0, v[100:101]
	global_load_dwordx4 v[100:103], v[100:101], off
	v_max3_f32 v0, v0, v136, v137
	v_mfma_f32_16x16x32_bf16 v[132:135], v[176:179], v[16:19], v[104:107]
	v_max3_f32 v0, v0, v138, v139
	s_nop 0
	v_max3_f32 v0, v0, v132, v133
	s_nop 0
	v_max3_f32 v0, v0, v134, v135
	s_nop 0
	v_lshl_add_u64 v[104:105], v[2:3], 0, v[164:165]
	v_lshl_add_u64 v[2:3], v[2:3], 0, v[166:167]
	global_load_dwordx4 v[104:107], v[104:105], off
	v_max_f32_e32 v151, v0, v0
	global_load_dwordx4 v[112:115], v[2:3], off
	v_max3_f32 v2, v128, v128, v129
	s_nop 0
	v_max3_f32 v2, v2, v130, v131
	s_nop 0
	v_max3_f32 v2, v2, v124, v125
	s_nop 0
	v_max3_f32 v2, v2, v126, v127
	s_nop 0
	v_max3_f32 v2, v2, v120, v121
	s_nop 0
	v_max3_f32 v2, v2, v122, v123
	s_nop 0
	v_max3_f32 v2, v2, v116, v117
	s_nop 0
	v_max3_f32 v2, v2, v118, v119
	s_nop 0
	v_max_f32_e32 v3, v2, v2
	v_max_f32_e32 v3, v151, v3
	v_cmp_lt_f32_e32 vcc, s94, v3
	s_cbranch_vccz .LBB0_1031
; template <int MODE, bool DEFER> ...
;     ...
;         if (__any(m0 > DEFER_THRESH || m1 > DEFER_THRESH)) {
;             m0 = fmaxf(qmax(m0), 0.f); m1 = fmaxf(qmax(m1), 0.f);
;             const float a0 = __builtin_amdgcn_exp2f(-m0), a1 = __builtin_amdgcn_exp2f(-m1);
;             mrun[0] += m0; mrun[1] += m1; lsum[0] *= a0; lsum[1] *= a1;
; #pragma unroll
;             for (int dt = 0; dt < 8; ++dt) { o[0][dt] = o[0][dt] * a0; o[1][dt] = o[1][dt] * a1; }
; #pragma unroll
;             for (int sub = 0; sub < 4; ++sub) { s[0][sub] = s[0][sub] - m0; s[1][sub] = s[1][sub] - m1; }
;         }
	v_mov_b32_e32 v3, v0
	s_nop 1
	v_permlane32_swap_b32_e32 v0, v3
	v_max_f32_e32 v3, v3, v3
	v_max_f32_e32 v0, v0, v0
	v_max_f32_e32 v0, v0, v3
	v_mov_b32_e32 v3, v0
	s_nop 1
	v_permlane16_swap_b32_e32 v0, v3
	v_max3_f32 v176, v0, v3, 0
	v_mov_b32_e32 v0, v2
	s_nop 1
	v_permlane32_swap_b32_e32 v2, v0
	v_max_f32_e32 v0, v0, v0
	v_max_f32_e32 v2, v2, v2
	v_max_f32_e32 v0, v2, v0
	v_mov_b32_e32 v2, v0
	s_nop 1
	v_permlane16_swap_b32_e32 v0, v2
	v_max3_f32 v177, v0, v2, 0
	v_exp_f32_e64 v3, -v176
	v_exp_f32_e64 v2, -v177
	v_pk_add_f32 v[174:175], v[174:175], v[176:177]
	v_sub_f32_e32 v144, v144, v176
	v_mov_b32_e32 v0, v3
	v_pk_mul_f32 v[170:171], v[170:171], v[2:3]
	v_pk_mul_f32 v[98:99], v[98:99], v[0:1] op_sel_hi:[1,0]
	v_pk_mul_f32 v[96:97], v[96:97], v[0:1] op_sel_hi:[1,0]
	v_pk_mul_f32 v[66:67], v[66:67], v[2:3] op_sel_hi:[1,0]
	v_pk_mul_f32 v[64:65], v[64:65], v[2:3] op_sel_hi:[1,0]
	v_pk_mul_f32 v[94:95], v[94:95], v[0:1] op_sel_hi:[1,0]
	v_pk_mul_f32 v[92:93], v[92:93], v[0:1] op_sel_hi:[1,0]
	v_pk_mul_f32 v[62:63], v[62:63], v[2:3] op_sel_hi:[1,0]
	v_pk_mul_f32 v[60:61], v[60:61], v[2:3] op_sel_hi:[1,0]
	v_pk_mul_f32 v[90:91], v[90:91], v[0:1] op_sel_hi:[1,0]
	v_pk_mul_f32 v[88:89], v[88:89], v[0:1] op_sel_hi:[1,0]
	v_pk_mul_f32 v[58:59], v[58:59], v[2:3] op_sel_hi:[1,0]
	v_pk_mul_f32 v[56:57], v[56:57], v[2:3] op_sel_hi:[1,0]
	v_pk_mul_f32 v[86:87], v[86:87], v[0:1] op_sel_hi:[1,0]
	v_pk_mul_f32 v[84:85], v[84:85], v[0:1] op_sel_hi:[1,0]
	v_pk_mul_f32 v[54:55], v[54:55], v[2:3] op_sel_hi:[1,0]
	v_pk_mul_f32 v[52:53], v[52:53], v[2:3] op_sel_hi:[1,0]
	v_pk_mul_f32 v[82:83], v[82:83], v[0:1] op_sel_hi:[1,0]
	v_pk_mul_f32 v[80:81], v[80:81], v[0:1] op_sel_hi:[1,0]
	v_pk_mul_f32 v[50:51], v[50:51], v[2:3] op_sel_hi:[1,0]
	v_pk_mul_f32 v[48:49], v[48:49], v[2:3] op_sel_hi:[1,0]
	v_pk_mul_f32 v[78:79], v[78:79], v[0:1] op_sel_hi:[1,0]
	v_pk_mul_f32 v[76:77], v[76:77], v[0:1] op_sel_hi:[1,0]
	v_pk_mul_f32 v[46:47], v[46:47], v[2:3] op_sel_hi:[1,0]
	v_pk_mul_f32 v[44:45], v[44:45], v[2:3] op_sel_hi:[1,0]
	v_pk_mul_f32 v[70:71], v[70:71], v[0:1] op_sel_hi:[1,0]
	v_pk_mul_f32 v[68:69], v[68:69], v[0:1] op_sel_hi:[1,0]
	v_pk_mul_f32 v[38:39], v[38:39], v[2:3] op_sel_hi:[1,0]
	v_pk_mul_f32 v[36:37], v[36:37], v[2:3] op_sel_hi:[1,0]
	v_pk_mul_f32 v[74:75], v[74:75], v[0:1] op_sel_hi:[1,0]
	v_pk_mul_f32 v[72:73], v[72:73], v[0:1] op_sel_hi:[1,0]
	v_pk_mul_f32 v[42:43], v[42:43], v[2:3] op_sel_hi:[1,0]
	v_pk_mul_f32 v[40:41], v[40:41], v[2:3] op_sel_hi:[1,0]
	v_sub_f32_e32 v145, v145, v176
	v_sub_f32_e32 v146, v146, v176
	v_sub_f32_e32 v147, v147, v176
	v_sub_f32_e32 v128, v128, v177
	v_sub_f32_e32 v129, v129, v177
	v_sub_f32_e32 v130, v130, v177
	v_sub_f32_e32 v131, v131, v177
	v_sub_f32_e32 v140, v140, v176
	v_sub_f32_e32 v141, v141, v176
	v_sub_f32_e32 v142, v142, v176
	v_sub_f32_e32 v143, v143, v176
	v_sub_f32_e32 v124, v124, v177
	v_sub_f32_e32 v125, v125, v177
	v_sub_f32_e32 v126, v126, v177
	v_sub_f32_e32 v127, v127, v177
	v_sub_f32_e32 v136, v136, v176
	v_sub_f32_e32 v137, v137, v176
	v_sub_f32_e32 v138, v138, v176
	v_sub_f32_e32 v139, v139, v176
	v_sub_f32_e32 v120, v120, v177
	v_sub_f32_e32 v121, v121, v177
	v_sub_f32_e32 v122, v122, v177
	v_sub_f32_e32 v123, v123, v177
	v_sub_f32_e32 v132, v132, v176
	v_sub_f32_e32 v133, v133, v176
	v_sub_f32_e32 v134, v134, v176
	v_sub_f32_e32 v135, v135, v176
	v_sub_f32_e32 v116, v116, v177
	v_sub_f32_e32 v117, v117, v177
	v_sub_f32_e32 v118, v118, v177
	v_sub_f32_e32 v119, v119, v177
	s_branch .LBB0_1031
